# adds: attention softmax row-sum block regenerated with scalar v_add_f32 (same association, symbolically verified) instead of half-junk v_pk_add_f32 + s_nop
# speedup vs baseline: 1.0162x; 1.0162x over previous
.LBB0_557:
	v_exp_f32_e32 v196, v80
	v_exp_f32_e32 v212, v64
	v_exp_f32_e32 v197, v81
	v_exp_f32_e32 v213, v65
	v_exp_f32_e32 v198, v82
	v_exp_f32_e32 v214, v66
	v_add_f32_e32 v229, v212, v196
	v_exp_f32_e32 v199, v83
	v_exp_f32_e32 v215, v67
	v_add_f32_e32 v230, v213, v197
	v_add_f32_e32 v229, v230, v229
	v_exp_f32_e32 v200, v84
	v_exp_f32_e32 v216, v68
	v_add_f32_e32 v228, v214, v198
	v_add_f32_e32 v229, v228, v229
	v_exp_f32_e32 v201, v85
	v_exp_f32_e32 v217, v69
	v_add_f32_e32 v230, v215, v199
	v_add_f32_e32 v229, v230, v229
	v_exp_f32_e32 v202, v86
	v_exp_f32_e32 v218, v70
	v_add_f32_e32 v228, v216, v200
	v_add_f32_e32 v229, v228, v229
	v_exp_f32_e32 v203, v87
	v_exp_f32_e32 v219, v71
	v_add_f32_e32 v230, v217, v201
	v_add_f32_e32 v229, v230, v229
	v_exp_f32_e32 v204, v88
	v_exp_f32_e32 v220, v72
	v_add_f32_e32 v228, v218, v202
	v_add_f32_e32 v229, v228, v229
	v_exp_f32_e32 v205, v89
	v_exp_f32_e32 v221, v73
	v_add_f32_e32 v230, v219, v203
	v_add_f32_e32 v229, v230, v229
	v_exp_f32_e32 v206, v90
	v_exp_f32_e32 v222, v74
	v_add_f32_e32 v228, v220, v204
	v_add_f32_e32 v229, v228, v229
	v_exp_f32_e32 v207, v91
	v_exp_f32_e32 v223, v75
	v_add_f32_e32 v230, v221, v205
	v_add_f32_e32 v229, v230, v229
	v_exp_f32_e32 v208, v92
	v_exp_f32_e32 v224, v76
	v_add_f32_e32 v228, v222, v206
	v_add_f32_e32 v229, v228, v229
	v_exp_f32_e32 v209, v93
	v_exp_f32_e32 v225, v77
	v_add_f32_e32 v230, v223, v207
	v_add_f32_e32 v229, v230, v229
	v_exp_f32_e32 v210, v94
	v_exp_f32_e32 v226, v78
	v_add_f32_e32 v228, v224, v208
	v_add_f32_e32 v229, v228, v229
	v_exp_f32_e32 v211, v95
	v_exp_f32_e32 v227, v79
	v_add_f32_e32 v230, v225, v209
	v_add_f32_e32 v229, v230, v229
	v_add_f32_e32 v228, v226, v210
	v_add_f32_e32 v229, v228, v229
	v_add_f32_e32 v230, v227, v211
	v_add_f32_e32 v95, v230, v229
	v_cvt_pk_bf16_f32 v64, v196, v197
	v_cvt_pk_bf16_f32 v65, v198, v199
	v_cvt_pk_bf16_f32 v66, v200, v201
	v_cvt_pk_bf16_f32 v67, v202, v203
	v_cvt_pk_bf16_f32 v68, v204, v205
	v_cvt_pk_bf16_f32 v69, v206, v207
	v_cvt_pk_bf16_f32 v70, v208, v209
	v_cvt_pk_bf16_f32 v71, v210, v211
	v_cvt_pk_bf16_f32 v72, v212, v213
	v_cvt_pk_bf16_f32 v73, v214, v215
	v_cvt_pk_bf16_f32 v74, v216, v217
	v_cvt_pk_bf16_f32 v75, v218, v219
	v_cvt_pk_bf16_f32 v76, v220, v221
	v_cvt_pk_bf16_f32 v77, v222, v223
	v_cvt_pk_bf16_f32 v78, v224, v225
	v_cvt_pk_bf16_f32 v79, v226, v227
	s_waitcnt lgkmcnt(0)
	v_mfma_f32_32x32x16_bf16 v[32:47], v[148:151], v[64:67], v[32:47]
	v_add_f32_e32 v159, v159, v95
	v_mfma_f32_32x32x16_bf16 v[16:31], v[132:135], v[64:67], v[16:31]
	v_mfma_f32_32x32x16_bf16 v[32:47], v[144:147], v[68:71], v[32:47]
	v_mfma_f32_32x32x16_bf16 v[16:31], v[128:131], v[68:71], v[16:31]
	v_mfma_f32_32x32x16_bf16 v[32:47], v[140:143], v[72:75], v[32:47]
	v_mfma_f32_32x32x16_bf16 v[16:31], v[10:13], v[72:75], v[16:31]
	v_mfma_f32_32x32x16_bf16 v[32:47], v[136:139], v[76:79], v[32:47]
	v_mfma_f32_32x32x16_bf16 v[16:31], v[6:9], v[76:79], v[16:31]
